# speedup vs baseline: 1.0259x; 1.0019x over previous
; __device__ __forceinline__ unsigned cvt_pk_bf16(float lo, float hi) { unsigned r; asm volatile("v_cvt_pk_bf16_f32 %0, %1, %2" : "=v"(r) : "v"(lo), "v"(hi)); return r; }
;     __device__ __forceinline__ void operator()(const f32x4 (&acc)[2][2][4][2], const Unit& u, int wr, int wc, int fr, int fq) const {
;     ...
;         const int row0 = u.pm * BM + wr * 64 + fr, col0 = u.pn * BM + wc * 32 + 8 * fq;
; #pragma unroll
;         for (int ai = 0; ai < 2; ++ai) {
;             u32x4 xv[4][2];
; #pragma unroll
;             for (int m = 0; m < 4; ++m)
; #pragma unroll
;                 for (int bj = 0; bj < 2; ++bj) xv[m][bj] = *(const u32x4*)(X + (size_t)(row0 + ai * HALF + m * 16) * ldc + col0 + bj * HALF);
;             asm volatile("" ::: "memory");
; #pragma unroll
;             for (int m = 0; m < 4; ++m) { const int row = row0 + ai * HALF + m * 16; bf16_t* rowp = X + (size_t)row * ldc + col0;
;                 float part = 0.f;
; #pragma unroll
;                 for (int bj = 0; bj < 2; ++bj) { const u32x4 x4 = xv[m][bj];
;                     const f32x4 a0 = acc[ai][bj][m][0], a1 = acc[ai][bj][m][1];
;                     const float f0 = bflo(x4.x) + a0[0], f1 = bfhi(x4.x) + a0[1], f2 = bflo(x4.y) + a0[2], f3 = bfhi(x4.y) + a0[3];
;                     const float f4 = bflo(x4.z) + a1[0], f5 = bfhi(x4.z) + a1[1], f6 = bflo(x4.w) + a1[2], f7 = bfhi(x4.w) + a1[3];
;                     part += (f0 * f0 + f1 * f1) + (f2 * f2 + f3 * f3) + (f4 * f4 + f5 * f5) + (f6 * f6 + f7 * f7);
;                     u32x4 w; w.x = cvt_pk_bf16(f0, f1); w.y = cvt_pk_bf16(f2, f3); w.z = cvt_pk_bf16(f4, f5); w.w = cvt_pk_bf16(f6, f7);
;                     *(u32x4*)(rowp + bj * HALF) = w; }
;                 part += __shfl_xor(part, 16); part += __shfl_xor(part, 32);
;                 if (fq == 0) SS[(size_t)row * 32 + u.pn * 4 + wc] = part; }
.LBB0_553:
	s_lshl_b32 s5, s22, 8
	v_mov_b32_e32 v128, v200
	v_mov_b32_e32 v134, v199
	s_add_i32 s5, s5, s62
	s_nop 7
	s_nop 7
	s_lshl_b32 s22, s4, 2
	v_add_u32_e32 v184, s5, v128
	s_lshl_b32 s5, s4, 8
	s_or_b32 s5, s5, s63
	v_lshl_add_u32 v180, v134, 3, s5
	v_ashrrev_i32_e32 v181, 31, v180
	v_lshlrev_b64 v[128:129], 1, v[180:181]
	v_ashrrev_i32_e32 v185, 31, v184
	v_lshl_add_u64 v[182:183], s[8:9], 0, v[128:129]
	v_lshlrev_b64 v[130:131], 12, v[184:185]
	v_lshl_add_u64 v[132:133], v[182:183], 0, v[130:131]
	global_load_dwordx4 v[204:207], v[132:133], off
	global_load_dwordx4 v[208:211], v[132:133], off offset:256
	v_add_u32_e32 v190, 16, v184
	v_add_u32_e32 v188, 32, v184
	v_add_u32_e32 v186, 48, v184
	v_ashrrev_i32_e32 v191, 31, v190
	v_ashrrev_i32_e32 v189, 31, v188
	v_cmp_eq_u32_e32 vcc, 0, v134
	v_ashrrev_i32_e32 v187, 31, v186
	v_lshlrev_b64 v[132:133], 12, v[190:191]
	v_lshlrev_b64 v[134:135], 12, v[188:189]
	v_lshlrev_b64 v[136:137], 12, v[186:187]
	v_lshl_add_u64 v[130:131], s[8:9], 0, v[130:131]
	v_lshl_add_u64 v[132:133], v[182:183], 0, v[132:133]
	v_lshl_add_u64 v[134:135], v[182:183], 0, v[134:135]
	v_lshl_add_u64 v[212:213], v[182:183], 0, v[136:137]
	v_lshl_add_u64 v[214:215], v[130:131], 0, v[128:129]
	global_load_dwordx4 v[148:151], v[132:133], off
	global_load_dwordx4 v[144:147], v[132:133], off offset:256
	global_load_dwordx4 v[140:143], v[134:135], off
	global_load_dwordx4 v[136:139], v[134:135], off offset:256
	s_nop 0
	global_load_dwordx4 v[132:135], v[212:213], off
	global_load_dwordx4 v[128:131], v[212:213], off offset:256
	v_add_u32_e32 v212, 0x80, v184
	v_ashrrev_i32_e32 v213, 31, v212
	v_lshlrev_b64 v[212:213], 12, v[212:213]
	v_lshl_add_u64 v[212:213], v[182:183], 0, v[212:213]
	global_load_dwordx4 v[222:225], v[212:213], off
	global_load_dwordx4 v[226:229], v[212:213], off offset:256
	v_add_u32_e32 v212, 0x90, v184
	v_ashrrev_i32_e32 v213, 31, v212
	v_lshlrev_b64 v[212:213], 12, v[212:213]
	v_lshl_add_u64 v[212:213], v[182:183], 0, v[212:213]
	global_load_dwordx4 v[230:233], v[212:213], off
	global_load_dwordx4 v[234:237], v[212:213], off offset:256
	v_add_u32_e32 v212, 0xa0, v184
	v_ashrrev_i32_e32 v213, 31, v212
	v_lshlrev_b64 v[212:213], 12, v[212:213]
	v_lshl_add_u64 v[212:213], v[182:183], 0, v[212:213]
	global_load_dwordx4 v[238:241], v[212:213], off
	global_load_dwordx4 v[244:247], v[212:213], off offset:256
	v_add_u32_e32 v212, 0xb0, v184
	v_ashrrev_i32_e32 v213, 31, v212
	v_lshlrev_b64 v[212:213], 12, v[212:213]
	v_lshl_add_u64 v[212:213], v[182:183], 0, v[212:213]
	global_load_dwordx4 v[248:251], v[212:213], off
	global_load_dwordx4 v[252:255], v[212:213], off offset:256
	s_ashr_i32 s23, s22, 31
	s_waitcnt vmcnt(8)
	v_lshlrev_b32_e32 v203, 16, v204
	v_and_b32_e32 v204, 0xffff0000, v204
	v_lshlrev_b32_e32 v212, 16, v205
	v_and_b32_e32 v205, 0xffff0000, v205
	v_lshlrev_b32_e32 v213, 16, v206
	v_and_b32_e32 v206, 0xffff0000, v206
	v_lshlrev_b32_e32 v217, 16, v208
	v_and_b32_e32 v208, 0xffff0000, v208
	v_lshlrev_b32_e32 v218, 16, v209
	v_and_b32_e32 v209, 0xffff0000, v209
	v_lshlrev_b32_e32 v219, 16, v210
	v_and_b32_e32 v210, 0xffff0000, v210
	v_add_f32_e32 v125, v125, v204
	v_add_f32_e32 v127, v127, v205
	v_lshlrev_b32_e32 v216, 16, v207
	v_and_b32_e32 v207, 0xffff0000, v207
	v_lshlrev_b32_e32 v220, 16, v211
	v_and_b32_e32 v211, 0xffff0000, v211
	v_add_f32_e32 v124, v124, v203
	v_add_f32_e32 v126, v126, v212
	v_add_f32_e32 v121, v121, v206
	v_add_f32_e32 v204, v117, v208
	v_add_f32_e32 v119, v119, v209
	v_add_f32_e32 v205, v112, v219
	v_add_f32_e32 v206, v113, v210
	v_mul_f32_e32 v112, v125, v125
	v_mul_f32_e32 v113, v127, v127
	v_add_f32_e32 v120, v120, v213
	v_add_f32_e32 v123, v123, v207
	v_add_f32_e32 v203, v116, v217
	v_add_f32_e32 v118, v118, v218
	v_add_f32_e32 v207, v114, v220
	v_add_f32_e32 v208, v115, v211
	v_mul_f32_e32 v116, v121, v121
	v_cvt_pk_bf16_f32 v114, v124, v125
	v_cvt_pk_bf16_f32 v115, v126, v127
	v_mul_f32_e32 v125, v204, v204
	v_mul_f32_e32 v127, v119, v119
	v_fmac_f32_e32 v112, v124, v124
	v_fmac_f32_e32 v113, v126, v126
	v_mul_f32_e32 v209, v206, v206
	v_fmac_f32_e32 v116, v120, v120
	v_fmac_f32_e32 v125, v203, v203
	v_fmac_f32_e32 v127, v118, v118
	v_add_f32_e32 v112, v112, v113
	v_add_f32_e32 v122, v122, v216
	v_mul_f32_e32 v117, v123, v123
	v_fmac_f32_e32 v209, v205, v205
	v_add_f32_e32 v113, v125, v127
	v_add_f32_e32 v112, v116, v112
	v_mul_f32_e32 v116, v208, v208
	v_fmac_f32_e32 v117, v122, v122
	v_add_f32_e32 v113, v209, v113
	v_fmac_f32_e32 v116, v207, v207
	v_add_f32_e32 v112, v117, v112
	v_add_f32_e32 v113, v116, v113
	v_and_b32_e32 v116, 64, v193
	v_add_f32_e32 v113, v112, v113
	v_xor_b32_e32 v112, 16, v193
	v_add_u32_e32 v124, 64, v116
	v_cmp_lt_i32_e64 s[4:5], v112, v124
	v_cvt_pk_bf16_f32 v116, v120, v121
	v_cvt_pk_bf16_f32 v117, v122, v123
	global_store_dwordx4 v[214:215], v[114:117], off
	s_nop 0
	v_cndmask_b32_e64 v112, v193, v112, s[4:5]
	v_lshlrev_b32_e32 v112, 2, v112
	ds_bpermute_b32 v125, v112, v113
	v_cvt_pk_bf16_f32 v116, v203, v204
	v_cvt_pk_bf16_f32 v117, v118, v119
	v_cvt_pk_bf16_f32 v118, v205, v206
	v_cvt_pk_bf16_f32 v119, v207, v208
	s_waitcnt lgkmcnt(0)
	v_add_f32_e32 v114, v113, v125
	v_xor_b32_e32 v113, 32, v193
	v_cmp_lt_i32_e64 s[4:5], v113, v124
	global_store_dwordx4 v[214:215], v[116:119], off offset:256
	s_nop 0
	v_cndmask_b32_e64 v113, v193, v113, s[4:5]
	v_lshlrev_b32_e32 v113, 2, v113
	ds_bpermute_b32 v115, v113, v114
	s_and_saveexec_b64 s[4:5], vcc
	s_cbranch_execz .LBB0_555
	v_lshlrev_b64 v[116:117], 7, v[184:185]
	v_lshl_add_u64 v[116:117], s[10:11], 0, v[116:117]
	v_lshl_add_u64 v[116:117], s[22:23], 2, v[116:117]
	s_lshl_b32 s76, s61, 2
	v_lshl_add_u64 v[116:117], v[116:117], 0, s[76:77]
	s_waitcnt lgkmcnt(0)
	v_add_f32_e32 v114, v114, v115
	global_store_dword v[116:117], v114, off

; __device__ __forceinline__ unsigned cvt_pk_bf16(float lo, float hi) { unsigned r; asm volatile("v_cvt_pk_bf16_f32 %0, %1, %2" : "=v"(r) : "v"(lo), "v"(hi)); return r; }
;     __device__ __forceinline__ void operator()(const f32x4 (&acc)[2][2][4][2], const Unit& u, int wr, int wc, int fr, int fq) const {
;     ...
;         for (int ai = 0; ai < 2; ++ai) {
;             u32x4 xv[4][2];
; #pragma unroll
;             for (int m = 0; m < 4; ++m)
; #pragma unroll
;                 for (int bj = 0; bj < 2; ++bj) xv[m][bj] = *(const u32x4*)(X + (size_t)(row0 + ai * HALF + m * 16) * ldc + col0 + bj * HALF);
;             asm volatile("" ::: "memory");
; #pragma unroll
;             for (int m = 0; m < 4; ++m) { const int row = row0 + ai * HALF + m * 16; bf16_t* rowp = X + (size_t)row * ldc + col0;
;                 float part = 0.f;
; #pragma unroll
;                 for (int bj = 0; bj < 2; ++bj) { const u32x4 x4 = xv[m][bj];
;                     const f32x4 a0 = acc[ai][bj][m][0], a1 = acc[ai][bj][m][1];
;                     const float f0 = bflo(x4.x) + a0[0], f1 = bfhi(x4.x) + a0[1], f2 = bflo(x4.y) + a0[2], f3 = bfhi(x4.y) + a0[3];
;                     const float f4 = bflo(x4.z) + a1[0], f5 = bfhi(x4.z) + a1[1], f6 = bflo(x4.w) + a1[2], f7 = bfhi(x4.w) + a1[3];
;                     part += (f0 * f0 + f1 * f1) + (f2 * f2 + f3 * f3) + (f4 * f4 + f5 * f5) + (f6 * f6 + f7 * f7);
;                     u32x4 w; w.x = cvt_pk_bf16(f0, f1); w.y = cvt_pk_bf16(f2, f3); w.z = cvt_pk_bf16(f4, f5); w.w = cvt_pk_bf16(f6, f7);
;                     *(u32x4*)(rowp + bj * HALF) = w; }
;                 part += __shfl_xor(part, 16); part += __shfl_xor(part, 32);
;                 if (fq == 0) SS[(size_t)row * 32 + u.pn * 4 + wc] = part; }
.LBB0_561:
	s_or_b64 exec, exec, s[4:5]
	v_add_u32_e32 v98, 0x80, v184
	v_ashrrev_i32_e32 v99, 31, v98
	v_lshlrev_b64 v[100:101], 12, v[98:99]
	s_waitcnt lgkmcnt(0)
	v_lshl_add_u64 v[64:65], v[182:183], 0, v[100:101]
	s_waitcnt vmcnt(12)
	v_mov_b32_e32 v102, v222
	v_mov_b32_e32 v103, v223
	v_mov_b32_e32 v104, v224
	v_mov_b32_e32 v105, v225
	v_mov_b32_e32 v88, v226
	v_mov_b32_e32 v89, v227
	v_mov_b32_e32 v90, v228
	v_mov_b32_e32 v91, v229
	v_add_u32_e32 v96, 0x90, v184
	v_ashrrev_i32_e32 v97, 31, v96
	v_lshlrev_b64 v[64:65], 12, v[96:97]
	v_add_u32_e32 v94, 0xa0, v184
	v_lshl_add_u64 v[64:65], v[182:183], 0, v[64:65]
	v_ashrrev_i32_e32 v95, 31, v94
	v_mov_b32_e32 v84, v230
	v_mov_b32_e32 v85, v231
	v_mov_b32_e32 v86, v232
	v_mov_b32_e32 v87, v233
	v_mov_b32_e32 v80, v234
	v_mov_b32_e32 v81, v235
	v_mov_b32_e32 v82, v236
	v_mov_b32_e32 v83, v237
	v_lshlrev_b64 v[64:65], 12, v[94:95]
	v_add_u32_e32 v92, 0xb0, v184
	v_lshl_add_u64 v[64:65], v[182:183], 0, v[64:65]
	v_ashrrev_i32_e32 v93, 31, v92
	v_mov_b32_e32 v76, v238
	v_mov_b32_e32 v77, v239
	v_mov_b32_e32 v78, v240
	v_mov_b32_e32 v79, v241
	v_mov_b32_e32 v72, v244
	v_mov_b32_e32 v73, v245
	v_mov_b32_e32 v74, v246
	v_mov_b32_e32 v75, v247
	v_lshlrev_b64 v[64:65], 12, v[92:93]
	v_lshl_add_u64 v[64:65], v[182:183], 0, v[64:65]
	v_mov_b32_e32 v68, v248
	v_mov_b32_e32 v69, v249
	v_mov_b32_e32 v70, v250
	v_mov_b32_e32 v71, v251
	s_nop 0
	v_mov_b32_e32 v64, v252
	v_mov_b32_e32 v65, v253
	v_mov_b32_e32 v66, v254
	v_mov_b32_e32 v67, v255
	v_lshl_add_u64 v[100:101], s[8:9], 0, v[100:101]
	v_lshl_add_u64 v[100:101], v[180:181], 1, v[100:101]
	v_lshlrev_b32_e32 v106, 16, v102
	v_and_b32_e32 v102, 0xffff0000, v102
	v_add_f32_e32 v61, v61, v102
	v_lshlrev_b32_e32 v102, 16, v103
	v_add_f32_e32 v62, v62, v102
	v_and_b32_e32 v102, 0xffff0000, v103
	v_add_f32_e32 v63, v63, v102
	v_lshlrev_b32_e32 v102, 16, v104
	v_add_f32_e32 v102, v56, v102
	v_and_b32_e32 v56, 0xffff0000, v104
	v_add_f32_e32 v103, v57, v56
	v_lshlrev_b32_e32 v56, 16, v105
	v_add_f32_e32 v104, v58, v56
	v_and_b32_e32 v56, 0xffff0000, v105
	v_add_f32_e32 v60, v60, v106
	v_add_f32_e32 v59, v59, v56
	v_mul_f32_e32 v56, v61, v61
	v_mul_f32_e32 v57, v63, v63
	v_fmac_f32_e32 v56, v60, v60
	v_fmac_f32_e32 v57, v62, v62
	v_add_f32_e32 v56, v56, v57
	v_mul_f32_e32 v57, v103, v103
	v_fmac_f32_e32 v57, v102, v102
	v_add_f32_e32 v56, v57, v56
	v_mul_f32_e32 v57, v59, v59
	v_fmac_f32_e32 v57, v104, v104
	v_add_f32_e32 v105, v57, v56
	v_cvt_pk_bf16_f32 v56, v60, v61
	v_cvt_pk_bf16_f32 v57, v62, v63
	v_cvt_pk_bf16_f32 v58, v102, v103
	v_cvt_pk_bf16_f32 v59, v104, v59
	global_store_dwordx4 v[100:101], v[56:59], off
	s_nop 0
	v_lshlrev_b32_e32 v56, 16, v88
	v_add_f32_e32 v52, v52, v56
	v_and_b32_e32 v56, 0xffff0000, v88
	v_add_f32_e32 v53, v53, v56
	v_lshlrev_b32_e32 v56, 16, v89
	v_add_f32_e32 v54, v54, v56
	v_and_b32_e32 v56, 0xffff0000, v89
	v_add_f32_e32 v55, v55, v56
	v_lshlrev_b32_e32 v56, 16, v90
	v_add_f32_e32 v56, v48, v56
	v_and_b32_e32 v48, 0xffff0000, v90
	v_add_f32_e32 v57, v49, v48
	v_lshlrev_b32_e32 v48, 16, v91
	v_add_f32_e32 v58, v50, v48
	v_and_b32_e32 v48, 0xffff0000, v91
	v_add_f32_e32 v51, v51, v48
	v_mul_f32_e32 v48, v53, v53
	v_mul_f32_e32 v49, v55, v55
	v_fmac_f32_e32 v48, v52, v52
	v_fmac_f32_e32 v49, v54, v54
	v_add_f32_e32 v48, v48, v49
	v_mul_f32_e32 v49, v57, v57
	v_fmac_f32_e32 v49, v56, v56
	v_add_f32_e32 v48, v49, v48
	v_mul_f32_e32 v49, v51, v51
	v_fmac_f32_e32 v49, v58, v58
	v_add_f32_e32 v48, v49, v48
	v_add_f32_e32 v59, v105, v48
	v_cvt_pk_bf16_f32 v48, v52, v53
	v_cvt_pk_bf16_f32 v49, v54, v55
	v_cvt_pk_bf16_f32 v50, v56, v57
	v_cvt_pk_bf16_f32 v51, v58, v51
	global_store_dwordx4 v[100:101], v[48:51], off offset:256
	ds_bpermute_b32 v48, v112, v59
	s_waitcnt lgkmcnt(0)
	v_add_f32_e32 v48, v59, v48
	ds_bpermute_b32 v49, v113, v48
	s_and_saveexec_b64 s[4:5], vcc
	s_cbranch_execz .LBB0_563
	v_lshlrev_b64 v[50:51], 7, v[98:99]
	v_lshl_add_u64 v[50:51], s[10:11], 0, v[50:51]
	v_lshl_add_u64 v[50:51], s[22:23], 2, v[50:51]
	s_lshl_b32 s76, s61, 2
	v_lshl_add_u64 v[50:51], v[50:51], 0, s[76:77]
	s_waitcnt lgkmcnt(0)
	v_add_f32_e32 v48, v48, v49
	global_store_dword v[50:51], v48, off
.LBB0_563:
	s_or_b64 exec, exec, s[4:5]
	v_lshlrev_b32_e32 v50, 16, v84
	v_add_f32_e32 v44, v44, v50
	v_and_b32_e32 v50, 0xffff0000, v84
	v_add_f32_e32 v45, v45, v50
	v_lshlrev_b32_e32 v50, 16, v85
	v_add_f32_e32 v46, v46, v50
	v_and_b32_e32 v50, 0xffff0000, v85
	v_add_f32_e32 v47, v47, v50
	v_lshlrev_b32_e32 v50, 16, v86
	v_add_f32_e32 v50, v40, v50
	v_and_b32_e32 v40, 0xffff0000, v86
	v_add_f32_e32 v51, v41, v40
	v_lshlrev_b32_e32 v40, 16, v87
	v_add_f32_e32 v52, v42, v40
	v_and_b32_e32 v40, 0xffff0000, v87
	v_add_f32_e32 v43, v43, v40
	v_mul_f32_e32 v40, v45, v45
	v_mul_f32_e32 v41, v47, v47
	v_fmac_f32_e32 v40, v44, v44
	v_fmac_f32_e32 v41, v46, v46
	v_add_f32_e32 v40, v40, v41
	v_mul_f32_e32 v41, v51, v51
	v_fmac_f32_e32 v41, v50, v50
	v_add_f32_e32 v40, v41, v40
	v_mul_f32_e32 v41, v43, v43
	v_fmac_f32_e32 v41, v52, v52
	v_add_f32_e32 v42, v41, v40
	v_cvt_pk_bf16_f32 v40, v44, v45
	v_lshlrev_b32_e32 v44, 16, v80
	v_add_f32_e32 v36, v36, v44
	v_and_b32_e32 v44, 0xffff0000, v80
	v_add_f32_e32 v37, v37, v44
	v_lshlrev_b32_e32 v44, 16, v81
	v_add_f32_e32 v38, v38, v44
	v_and_b32_e32 v44, 0xffff0000, v81
	v_add_f32_e32 v39, v39, v44
	v_lshlrev_b32_e32 v44, 16, v82
	v_add_f32_e32 v44, v32, v44
	v_and_b32_e32 v32, 0xffff0000, v82
	v_add_f32_e32 v45, v33, v32
	v_lshlrev_b32_e32 v32, 16, v83
	v_cvt_pk_bf16_f32 v41, v46, v47
	v_add_f32_e32 v46, v34, v32
	v_and_b32_e32 v32, 0xffff0000, v83
	v_add_f32_e32 v47, v35, v32
	v_mul_f32_e32 v32, v37, v37
	v_mul_f32_e32 v33, v39, v39
	v_fmac_f32_e32 v32, v36, v36
	v_fmac_f32_e32 v33, v38, v38
	v_add_f32_e32 v32, v32, v33
	v_mul_f32_e32 v33, v45, v45
	v_fmac_f32_e32 v33, v44, v44
	v_add_f32_e32 v32, v33, v32
	v_mul_f32_e32 v33, v47, v47
	v_fmac_f32_e32 v33, v46, v46
	v_add_f32_e32 v32, v33, v32
	v_add_f32_e32 v32, v42, v32
	ds_bpermute_b32 v33, v112, v32
	s_waitcnt lgkmcnt(1)
	v_lshlrev_b64 v[48:49], 11, v[96:97]
	v_lshl_add_u64 v[48:49], v[48:49], 1, s[8:9]
	v_lshl_add_u64 v[48:49], v[180:181], 1, v[48:49]
	v_cvt_pk_bf16_f32 v42, v50, v51
	s_waitcnt lgkmcnt(0)
	v_add_f32_e32 v32, v32, v33
	ds_bpermute_b32 v33, v113, v32
	v_cvt_pk_bf16_f32 v43, v52, v43
	global_store_dwordx4 v[48:49], v[40:43], off
	v_cvt_pk_bf16_f32 v34, v36, v37
	v_cvt_pk_bf16_f32 v35, v38, v39
	v_cvt_pk_bf16_f32 v36, v44, v45
	v_cvt_pk_bf16_f32 v37, v46, v47
	global_store_dwordx4 v[48:49], v[34:37], off offset:256
	s_and_saveexec_b64 s[4:5], vcc
	s_cbranch_execz .LBB0_565
	v_lshlrev_b64 v[34:35], 7, v[96:97]
	v_lshl_add_u64 v[34:35], s[10:11], 0, v[34:35]
	v_lshl_add_u64 v[34:35], s[22:23], 2, v[34:35]
	s_lshl_b32 s76, s61, 2
	v_lshl_add_u64 v[34:35], v[34:35], 0, s[76:77]
	s_waitcnt lgkmcnt(0)
	v_add_f32_e32 v32, v32, v33
	global_store_dword v[34:35], v32, off
; __device__ __forceinline__ unsigned cvt_pk_bf16(float lo, float hi) { unsigned r; asm volatile("v_cvt_pk_bf16_f32 %0, %1, %2" : "=v"(r) : "v"(lo), "v"(hi)); return r; }
;     __device__ __forceinline__ void operator()(const f32x4 (&acc)[2][2][4][2], const Unit& u, int wr, int wc, int fr, int fq) const {
;     ...
;             for (int m = 0; m < 4; ++m) { const int row = row0 + ai * HALF + m * 16; bf16_t* rowp = X + (size_t)row * ldc + col0;
;                 float part = 0.f;
; #pragma unroll
;                 for (int bj = 0; bj < 2; ++bj) { const u32x4 x4 = xv[m][bj];
;                     const f32x4 a0 = acc[ai][bj][m][0], a1 = acc[ai][bj][m][1];
;                     const float f0 = bflo(x4.x) + a0[0], f1 = bfhi(x4.x) + a0[1], f2 = bflo(x4.y) + a0[2], f3 = bfhi(x4.y) + a0[3];
;                     const float f4 = bflo(x4.z) + a1[0], f5 = bfhi(x4.z) + a1[1], f6 = bflo(x4.w) + a1[2], f7 = bfhi(x4.w) + a1[3];
;                     part += (f0 * f0 + f1 * f1) + (f2 * f2 + f3 * f3) + (f4 * f4 + f5 * f5) + (f6 * f6 + f7 * f7);
;                     u32x4 w; w.x = cvt_pk_bf16(f0, f1); w.y = cvt_pk_bf16(f2, f3); w.z = cvt_pk_bf16(f4, f5); w.w = cvt_pk_bf16(f6, f7);
;                     *(u32x4*)(rowp + bj * HALF) = w; }
;                 part += __shfl_xor(part, 16); part += __shfl_xor(part, 32);
;                 if (fq == 0) SS[(size_t)row * 32 + u.pn * 4 + wc] = part; }
.LBB0_565:
	s_or_b64 exec, exec, s[4:5]
	v_lshlrev_b32_e32 v34, 16, v76
	v_add_f32_e32 v28, v28, v34
	v_and_b32_e32 v34, 0xffff0000, v76
	v_add_f32_e32 v29, v29, v34
	v_lshlrev_b32_e32 v34, 16, v77
	v_add_f32_e32 v30, v30, v34
	v_and_b32_e32 v34, 0xffff0000, v77
	v_add_f32_e32 v31, v31, v34
	v_lshlrev_b32_e32 v34, 16, v78
	v_add_f32_e32 v34, v24, v34
	v_and_b32_e32 v24, 0xffff0000, v78
	v_add_f32_e32 v35, v25, v24
	v_lshlrev_b32_e32 v24, 16, v79
	v_add_f32_e32 v36, v26, v24
	v_and_b32_e32 v24, 0xffff0000, v79
	v_add_f32_e32 v27, v27, v24
	v_mul_f32_e32 v24, v29, v29
	v_mul_f32_e32 v25, v31, v31
	v_fmac_f32_e32 v24, v28, v28
	v_fmac_f32_e32 v25, v30, v30
	v_add_f32_e32 v24, v24, v25
	v_mul_f32_e32 v25, v35, v35
	v_fmac_f32_e32 v25, v34, v34
	v_add_f32_e32 v24, v25, v24
	v_mul_f32_e32 v25, v27, v27
	v_fmac_f32_e32 v25, v36, v36
	v_add_f32_e32 v26, v25, v24
	v_cvt_pk_bf16_f32 v24, v28, v29
	v_lshlrev_b32_e32 v28, 16, v72
	v_add_f32_e32 v20, v20, v28
	v_and_b32_e32 v28, 0xffff0000, v72
	v_add_f32_e32 v21, v21, v28
	v_lshlrev_b32_e32 v28, 16, v73
	v_add_f32_e32 v22, v22, v28
	v_and_b32_e32 v28, 0xffff0000, v73
	v_add_f32_e32 v23, v23, v28
	v_lshlrev_b32_e32 v28, 16, v74
	v_add_f32_e32 v28, v16, v28
	v_and_b32_e32 v16, 0xffff0000, v74
	v_add_f32_e32 v29, v17, v16
	v_lshlrev_b32_e32 v16, 16, v75
	v_cvt_pk_bf16_f32 v25, v30, v31
	v_add_f32_e32 v30, v18, v16
	v_and_b32_e32 v16, 0xffff0000, v75
	v_add_f32_e32 v31, v19, v16
	v_mul_f32_e32 v16, v21, v21
	v_mul_f32_e32 v17, v23, v23
	v_fmac_f32_e32 v16, v20, v20
	v_fmac_f32_e32 v17, v22, v22
	v_add_f32_e32 v16, v16, v17
	v_mul_f32_e32 v17, v29, v29
	v_fmac_f32_e32 v17, v28, v28
	v_add_f32_e32 v16, v17, v16
	v_mul_f32_e32 v17, v31, v31
	v_fmac_f32_e32 v17, v30, v30
	v_add_f32_e32 v16, v17, v16
	v_add_f32_e32 v16, v26, v16
	ds_bpermute_b32 v17, v112, v16
	s_waitcnt lgkmcnt(1)
	v_lshlrev_b64 v[32:33], 11, v[94:95]
	v_lshl_add_u64 v[32:33], v[32:33], 1, s[8:9]
	v_lshl_add_u64 v[32:33], v[180:181], 1, v[32:33]
	v_cvt_pk_bf16_f32 v26, v34, v35
	s_waitcnt lgkmcnt(0)
	v_add_f32_e32 v16, v16, v17
	ds_bpermute_b32 v17, v113, v16
	v_cvt_pk_bf16_f32 v27, v36, v27
	global_store_dwordx4 v[32:33], v[24:27], off
	v_cvt_pk_bf16_f32 v18, v20, v21
	v_cvt_pk_bf16_f32 v19, v22, v23
	v_cvt_pk_bf16_f32 v20, v28, v29
	v_cvt_pk_bf16_f32 v21, v30, v31
	global_store_dwordx4 v[32:33], v[18:21], off offset:256
	s_and_saveexec_b64 s[4:5], vcc
	s_cbranch_execz .LBB0_567
	v_lshlrev_b64 v[18:19], 7, v[94:95]
	v_lshl_add_u64 v[18:19], s[10:11], 0, v[18:19]
	v_lshl_add_u64 v[18:19], s[22:23], 2, v[18:19]
	s_lshl_b32 s76, s61, 2
	v_lshl_add_u64 v[18:19], v[18:19], 0, s[76:77]
	s_waitcnt lgkmcnt(0)
	v_add_f32_e32 v16, v16, v17
	global_store_dword v[18:19], v16, off
.LBB0_567:
	s_or_b64 exec, exec, s[4:5]
	v_lshlrev_b32_e32 v18, 16, v68
	v_add_f32_e32 v12, v12, v18
	v_and_b32_e32 v18, 0xffff0000, v68
	v_add_f32_e32 v13, v13, v18
	v_lshlrev_b32_e32 v18, 16, v69
	v_add_f32_e32 v14, v14, v18
	v_and_b32_e32 v18, 0xffff0000, v69
	v_add_f32_e32 v15, v15, v18
	v_lshlrev_b32_e32 v18, 16, v70
	v_add_f32_e32 v18, v8, v18
	v_and_b32_e32 v8, 0xffff0000, v70
	v_add_f32_e32 v19, v9, v8
	v_lshlrev_b32_e32 v8, 16, v71
	v_add_f32_e32 v20, v10, v8
	v_and_b32_e32 v8, 0xffff0000, v71
	v_add_f32_e32 v11, v11, v8
	v_mul_f32_e32 v8, v13, v13
	v_mul_f32_e32 v9, v15, v15
	v_fmac_f32_e32 v8, v12, v12
	v_fmac_f32_e32 v9, v14, v14
	v_add_f32_e32 v8, v8, v9
	v_mul_f32_e32 v9, v19, v19
	v_fmac_f32_e32 v9, v18, v18
	v_add_f32_e32 v8, v9, v8
	v_mul_f32_e32 v9, v11, v11
	v_fmac_f32_e32 v9, v20, v20
	v_add_f32_e32 v10, v9, v8
	v_cvt_pk_bf16_f32 v8, v12, v13
	v_lshlrev_b32_e32 v12, 16, v64
	v_add_f32_e32 v4, v4, v12
	v_and_b32_e32 v12, 0xffff0000, v64
	v_add_f32_e32 v5, v5, v12
	v_lshlrev_b32_e32 v12, 16, v65
	v_add_f32_e32 v6, v6, v12
	v_and_b32_e32 v12, 0xffff0000, v65
	v_add_f32_e32 v7, v7, v12
	v_lshlrev_b32_e32 v12, 16, v66
	v_add_f32_e32 v12, v0, v12
	v_and_b32_e32 v0, 0xffff0000, v66
	v_add_f32_e32 v13, v1, v0
	v_lshlrev_b32_e32 v0, 16, v67
	v_cvt_pk_bf16_f32 v9, v14, v15
	v_add_f32_e32 v14, v2, v0
	v_and_b32_e32 v0, 0xffff0000, v67
	v_add_f32_e32 v15, v3, v0
	v_mul_f32_e32 v0, v5, v5
	v_mul_f32_e32 v1, v7, v7
	v_fmac_f32_e32 v0, v4, v4
	v_fmac_f32_e32 v1, v6, v6
	v_add_f32_e32 v0, v0, v1
	v_mul_f32_e32 v1, v13, v13
	v_fmac_f32_e32 v1, v12, v12
	v_add_f32_e32 v0, v1, v0
	v_mul_f32_e32 v1, v15, v15
	v_fmac_f32_e32 v1, v14, v14
	v_add_f32_e32 v0, v1, v0
	v_add_f32_e32 v0, v10, v0
	ds_bpermute_b32 v1, v112, v0
	s_waitcnt lgkmcnt(1)
	v_lshlrev_b64 v[16:17], 11, v[92:93]
	v_lshl_add_u64 v[16:17], v[16:17], 1, s[8:9]
	v_lshl_add_u64 v[16:17], v[180:181], 1, v[16:17]
	v_cvt_pk_bf16_f32 v10, v18, v19
	s_waitcnt lgkmcnt(0)
	v_add_f32_e32 v0, v0, v1
	ds_bpermute_b32 v1, v113, v0
	v_cvt_pk_bf16_f32 v11, v20, v11
	global_store_dwordx4 v[16:17], v[8:11], off
	v_cvt_pk_bf16_f32 v2, v4, v5
	v_cvt_pk_bf16_f32 v3, v6, v7
	v_cvt_pk_bf16_f32 v4, v12, v13
	v_cvt_pk_bf16_f32 v5, v14, v15
	global_store_dwordx4 v[16:17], v[2:5], off offset:256
	s_and_saveexec_b64 s[4:5], vcc
	s_cbranch_execz .LBB0_569
	v_lshlrev_b64 v[2:3], 7, v[92:93]
	v_lshl_add_u64 v[2:3], s[10:11], 0, v[2:3]
	v_lshl_add_u64 v[2:3], s[22:23], 2, v[2:3]
	s_lshl_b32 s76, s61, 2
	v_lshl_add_u64 v[2:3], v[2:3], 0, s[76:77]
	s_waitcnt lgkmcnt(0)
	v_add_f32_e32 v0, v0, v1
	global_store_dword v[2:3], v0, off

; __device__ __forceinline__ unsigned cvt_pk_bf16(float lo, float hi) { unsigned r; asm volatile("v_cvt_pk_bf16_f32 %0, %1, %2" : "=v"(r) : "v"(lo), "v"(hi)); return r; }
;     __device__ __forceinline__ void operator()(const f32x4 (&acc)[2][2][4][2], const Unit& u, int wr, int wc, int fr, int fq) const {
;     ...
;         const int row0 = u.pm * BM + wr * 64 + fr, col0 = u.pn * BM + wc * 32 + 8 * fq;
; #pragma unroll
;         for (int ai = 0; ai < 2; ++ai) {
;             u32x4 xv[4][2];
; #pragma unroll
;             for (int m = 0; m < 4; ++m)
; #pragma unroll
;                 for (int bj = 0; bj < 2; ++bj) xv[m][bj] = *(const u32x4*)(X + (size_t)(row0 + ai * HALF + m * 16) * ldc + col0 + bj * HALF);
;             asm volatile("" ::: "memory");
; #pragma unroll
;             for (int m = 0; m < 4; ++m) { const int row = row0 + ai * HALF + m * 16; bf16_t* rowp = X + (size_t)row * ldc + col0;
;                 float part = 0.f;
; #pragma unroll
;                 for (int bj = 0; bj < 2; ++bj) { const u32x4 x4 = xv[m][bj];
;                     const f32x4 a0 = acc[ai][bj][m][0], a1 = acc[ai][bj][m][1];
;                     const float f0 = bflo(x4.x) + a0[0], f1 = bfhi(x4.x) + a0[1], f2 = bflo(x4.y) + a0[2], f3 = bfhi(x4.y) + a0[3];
;                     const float f4 = bflo(x4.z) + a1[0], f5 = bfhi(x4.z) + a1[1], f6 = bflo(x4.w) + a1[2], f7 = bfhi(x4.w) + a1[3];
;                     part += (f0 * f0 + f1 * f1) + (f2 * f2 + f3 * f3) + (f4 * f4 + f5 * f5) + (f6 * f6 + f7 * f7);
;                     u32x4 w; w.x = cvt_pk_bf16(f0, f1); w.y = cvt_pk_bf16(f2, f3); w.z = cvt_pk_bf16(f4, f5); w.w = cvt_pk_bf16(f6, f7);
;                     *(u32x4*)(rowp + bj * HALF) = w; }
;                 part += __shfl_xor(part, 16); part += __shfl_xor(part, 32);
;                 if (fq == 0) SS[(size_t)row * 32 + u.pn * 4 + wc] = part; }
.LBB0_766:
	s_lshl_b32 s4, s66, 8
	v_mov_b32_e32 v134, v199
	v_mov_b32_e32 v128, v200
	s_add_i32 s4, s4, s56
	s_nop 7
	s_nop 7
	s_lshl_b32 s18, s65, 2
	v_add_u32_e32 v184, s4, v128
	s_lshl_b32 s4, s65, 8
	s_or_b32 s4, s4, s57
	v_lshl_add_u32 v180, v134, 3, s4
	v_ashrrev_i32_e32 v181, 31, v180
	v_lshlrev_b64 v[128:129], 1, v[180:181]
	v_ashrrev_i32_e32 v185, 31, v184
	v_lshl_add_u64 v[182:183], s[8:9], 0, v[128:129]
	v_lshlrev_b64 v[130:131], 12, v[184:185]
	v_lshl_add_u64 v[132:133], v[182:183], 0, v[130:131]
	global_load_dwordx4 v[204:207], v[132:133], off
	global_load_dwordx4 v[208:211], v[132:133], off offset:256
	v_add_u32_e32 v190, 16, v184
	v_add_u32_e32 v188, 32, v184
	v_add_u32_e32 v186, 48, v184
	v_ashrrev_i32_e32 v191, 31, v190
	v_ashrrev_i32_e32 v189, 31, v188
	v_cmp_eq_u32_e32 vcc, 0, v134
	v_ashrrev_i32_e32 v187, 31, v186
	v_lshlrev_b64 v[132:133], 12, v[190:191]
	v_lshlrev_b64 v[134:135], 12, v[188:189]
	v_lshlrev_b64 v[136:137], 12, v[186:187]
	v_lshl_add_u64 v[130:131], s[8:9], 0, v[130:131]
	v_lshl_add_u64 v[132:133], v[182:183], 0, v[132:133]
	v_lshl_add_u64 v[134:135], v[182:183], 0, v[134:135]
	v_lshl_add_u64 v[212:213], v[182:183], 0, v[136:137]
	v_lshl_add_u64 v[214:215], v[130:131], 0, v[128:129]
	global_load_dwordx4 v[148:151], v[132:133], off
	global_load_dwordx4 v[144:147], v[132:133], off offset:256
	global_load_dwordx4 v[140:143], v[134:135], off
	global_load_dwordx4 v[136:139], v[134:135], off offset:256
	s_nop 0
	global_load_dwordx4 v[132:135], v[212:213], off
	global_load_dwordx4 v[128:131], v[212:213], off offset:256
	v_add_u32_e32 v212, 0x80, v184
	v_ashrrev_i32_e32 v213, 31, v212
	v_lshlrev_b64 v[212:213], 12, v[212:213]
	v_lshl_add_u64 v[212:213], v[182:183], 0, v[212:213]
	global_load_dwordx4 v[222:225], v[212:213], off
	global_load_dwordx4 v[226:229], v[212:213], off offset:256
	v_add_u32_e32 v212, 0x90, v184
	v_ashrrev_i32_e32 v213, 31, v212
	v_lshlrev_b64 v[212:213], 12, v[212:213]
	v_lshl_add_u64 v[212:213], v[182:183], 0, v[212:213]
	global_load_dwordx4 v[230:233], v[212:213], off
	global_load_dwordx4 v[234:237], v[212:213], off offset:256
	v_add_u32_e32 v212, 0xa0, v184
	v_ashrrev_i32_e32 v213, 31, v212
	v_lshlrev_b64 v[212:213], 12, v[212:213]
	v_lshl_add_u64 v[212:213], v[182:183], 0, v[212:213]
	global_load_dwordx4 v[238:241], v[212:213], off
	global_load_dwordx4 v[244:247], v[212:213], off offset:256
	v_add_u32_e32 v212, 0xb0, v184
	v_ashrrev_i32_e32 v213, 31, v212
	v_lshlrev_b64 v[212:213], 12, v[212:213]
	v_lshl_add_u64 v[212:213], v[182:183], 0, v[212:213]
	global_load_dwordx4 v[248:251], v[212:213], off
	global_load_dwordx4 v[252:255], v[212:213], off offset:256
	s_ashr_i32 s19, s18, 31
	s_waitcnt vmcnt(8)
	v_lshlrev_b32_e32 v203, 16, v204
	v_and_b32_e32 v204, 0xffff0000, v204
	v_lshlrev_b32_e32 v212, 16, v205
	v_and_b32_e32 v205, 0xffff0000, v205
	v_lshlrev_b32_e32 v213, 16, v206
	v_and_b32_e32 v206, 0xffff0000, v206
	v_lshlrev_b32_e32 v217, 16, v208
	v_and_b32_e32 v208, 0xffff0000, v208
	v_lshlrev_b32_e32 v218, 16, v209
	v_and_b32_e32 v209, 0xffff0000, v209
	v_lshlrev_b32_e32 v219, 16, v210
	v_and_b32_e32 v210, 0xffff0000, v210
	v_add_f32_e32 v125, v125, v204
	v_add_f32_e32 v127, v127, v205
	v_lshlrev_b32_e32 v216, 16, v207
	v_and_b32_e32 v207, 0xffff0000, v207
	v_lshlrev_b32_e32 v220, 16, v211
	v_and_b32_e32 v211, 0xffff0000, v211
	v_add_f32_e32 v124, v124, v203
	v_add_f32_e32 v126, v126, v212
	v_add_f32_e32 v121, v121, v206
	v_add_f32_e32 v204, v117, v208
	v_add_f32_e32 v119, v119, v209
	v_add_f32_e32 v205, v112, v219
	v_add_f32_e32 v206, v113, v210
	v_mul_f32_e32 v112, v125, v125
	v_mul_f32_e32 v113, v127, v127
	v_add_f32_e32 v120, v120, v213
	v_add_f32_e32 v123, v123, v207
	v_add_f32_e32 v203, v116, v217
	v_add_f32_e32 v118, v118, v218
	v_add_f32_e32 v207, v114, v220
	v_add_f32_e32 v208, v115, v211
	v_mul_f32_e32 v116, v121, v121
	v_cvt_pk_bf16_f32 v114, v124, v125
	v_cvt_pk_bf16_f32 v115, v126, v127
	v_mul_f32_e32 v125, v204, v204
	v_mul_f32_e32 v127, v119, v119
	v_fmac_f32_e32 v112, v124, v124
	v_fmac_f32_e32 v113, v126, v126
	v_mul_f32_e32 v209, v206, v206
	v_fmac_f32_e32 v116, v120, v120
	v_fmac_f32_e32 v125, v203, v203
	v_fmac_f32_e32 v127, v118, v118
	v_add_f32_e32 v112, v112, v113
	v_add_f32_e32 v122, v122, v216
	v_mul_f32_e32 v117, v123, v123
	v_fmac_f32_e32 v209, v205, v205
	v_add_f32_e32 v113, v125, v127
	v_add_f32_e32 v112, v116, v112
	v_mul_f32_e32 v116, v208, v208
	v_fmac_f32_e32 v117, v122, v122
	v_add_f32_e32 v113, v209, v113
	v_fmac_f32_e32 v116, v207, v207
	v_add_f32_e32 v112, v117, v112
	v_add_f32_e32 v113, v116, v113
	v_and_b32_e32 v116, 64, v193
	v_add_f32_e32 v113, v112, v113
	v_xor_b32_e32 v112, 16, v193
	v_add_u32_e32 v124, 64, v116
	v_cmp_lt_i32_e64 s[4:5], v112, v124
	v_cvt_pk_bf16_f32 v116, v120, v121
	v_cvt_pk_bf16_f32 v117, v122, v123
	global_store_dwordx4 v[214:215], v[114:117], off
	s_nop 0
	v_cndmask_b32_e64 v112, v193, v112, s[4:5]
	v_lshlrev_b32_e32 v112, 2, v112
	ds_bpermute_b32 v125, v112, v113
	v_cvt_pk_bf16_f32 v116, v203, v204
	v_cvt_pk_bf16_f32 v117, v118, v119
	v_cvt_pk_bf16_f32 v118, v205, v206
	v_cvt_pk_bf16_f32 v119, v207, v208
	s_waitcnt lgkmcnt(0)
	v_add_f32_e32 v114, v113, v125
	v_xor_b32_e32 v113, 32, v193
	v_cmp_lt_i32_e64 s[4:5], v113, v124
	global_store_dwordx4 v[214:215], v[116:119], off offset:256
	s_nop 0
	v_cndmask_b32_e64 v113, v193, v113, s[4:5]
	v_lshlrev_b32_e32 v113, 2, v113
	ds_bpermute_b32 v115, v113, v114
	s_and_saveexec_b64 s[4:5], vcc
	s_cbranch_execz .LBB0_768
	v_lshlrev_b64 v[116:117], 7, v[184:185]
	v_lshl_add_u64 v[116:117], s[10:11], 0, v[116:117]
	v_lshl_add_u64 v[116:117], s[18:19], 2, v[116:117]
	s_lshl_b32 s76, s55, 2
	v_lshl_add_u64 v[116:117], v[116:117], 0, s[76:77]
	s_waitcnt lgkmcnt(0)
	v_add_f32_e32 v114, v114, v115
	global_store_dword v[116:117], v114, off

; __device__ __forceinline__ unsigned cvt_pk_bf16(float lo, float hi) { unsigned r; asm volatile("v_cvt_pk_bf16_f32 %0, %1, %2" : "=v"(r) : "v"(lo), "v"(hi)); return r; }
;     __device__ __forceinline__ void operator()(const f32x4 (&acc)[2][2][4][2], const Unit& u, int wr, int wc, int fr, int fq) const {
;     ...
;         for (int ai = 0; ai < 2; ++ai) {
;             u32x4 xv[4][2];
; #pragma unroll
;             for (int m = 0; m < 4; ++m)
; #pragma unroll
;                 for (int bj = 0; bj < 2; ++bj) xv[m][bj] = *(const u32x4*)(X + (size_t)(row0 + ai * HALF + m * 16) * ldc + col0 + bj * HALF);
;             asm volatile("" ::: "memory");
; #pragma unroll
;             for (int m = 0; m < 4; ++m) { const int row = row0 + ai * HALF + m * 16; bf16_t* rowp = X + (size_t)row * ldc + col0;
;                 float part = 0.f;
; #pragma unroll
;                 for (int bj = 0; bj < 2; ++bj) { const u32x4 x4 = xv[m][bj];
;                     const f32x4 a0 = acc[ai][bj][m][0], a1 = acc[ai][bj][m][1];
;                     const float f0 = bflo(x4.x) + a0[0], f1 = bfhi(x4.x) + a0[1], f2 = bflo(x4.y) + a0[2], f3 = bfhi(x4.y) + a0[3];
;                     const float f4 = bflo(x4.z) + a1[0], f5 = bfhi(x4.z) + a1[1], f6 = bflo(x4.w) + a1[2], f7 = bfhi(x4.w) + a1[3];
;                     part += (f0 * f0 + f1 * f1) + (f2 * f2 + f3 * f3) + (f4 * f4 + f5 * f5) + (f6 * f6 + f7 * f7);
;                     u32x4 w; w.x = cvt_pk_bf16(f0, f1); w.y = cvt_pk_bf16(f2, f3); w.z = cvt_pk_bf16(f4, f5); w.w = cvt_pk_bf16(f6, f7);
;                     *(u32x4*)(rowp + bj * HALF) = w; }
;                 part += __shfl_xor(part, 16); part += __shfl_xor(part, 32);
;                 if (fq == 0) SS[(size_t)row * 32 + u.pn * 4 + wc] = part; }
.LBB0_774:
	s_or_b64 exec, exec, s[4:5]
	v_add_u32_e32 v98, 0x80, v184
	v_ashrrev_i32_e32 v99, 31, v98
	v_lshlrev_b64 v[100:101], 12, v[98:99]
	s_waitcnt lgkmcnt(0)
	v_lshl_add_u64 v[64:65], v[182:183], 0, v[100:101]
	s_waitcnt vmcnt(12)
	v_mov_b32_e32 v102, v222
	v_mov_b32_e32 v103, v223
	v_mov_b32_e32 v104, v224
	v_mov_b32_e32 v105, v225
	v_mov_b32_e32 v88, v226
	v_mov_b32_e32 v89, v227
	v_mov_b32_e32 v90, v228
	v_mov_b32_e32 v91, v229
	v_add_u32_e32 v96, 0x90, v184
	v_ashrrev_i32_e32 v97, 31, v96
	v_lshlrev_b64 v[64:65], 12, v[96:97]
	v_add_u32_e32 v94, 0xa0, v184
	v_lshl_add_u64 v[64:65], v[182:183], 0, v[64:65]
	v_ashrrev_i32_e32 v95, 31, v94
	v_mov_b32_e32 v84, v230
	v_mov_b32_e32 v85, v231
	v_mov_b32_e32 v86, v232
	v_mov_b32_e32 v87, v233
	v_mov_b32_e32 v80, v234
	v_mov_b32_e32 v81, v235
	v_mov_b32_e32 v82, v236
	v_mov_b32_e32 v83, v237
	v_lshlrev_b64 v[64:65], 12, v[94:95]
	v_add_u32_e32 v92, 0xb0, v184
	v_lshl_add_u64 v[64:65], v[182:183], 0, v[64:65]
	v_ashrrev_i32_e32 v93, 31, v92
	v_mov_b32_e32 v76, v238
	v_mov_b32_e32 v77, v239
	v_mov_b32_e32 v78, v240
	v_mov_b32_e32 v79, v241
	v_mov_b32_e32 v72, v244
	v_mov_b32_e32 v73, v245
	v_mov_b32_e32 v74, v246
	v_mov_b32_e32 v75, v247
	v_lshlrev_b64 v[64:65], 12, v[92:93]
	v_lshl_add_u64 v[64:65], v[182:183], 0, v[64:65]
	v_mov_b32_e32 v68, v248
	v_mov_b32_e32 v69, v249
	v_mov_b32_e32 v70, v250
	v_mov_b32_e32 v71, v251
	s_nop 0
	v_mov_b32_e32 v64, v252
	v_mov_b32_e32 v65, v253
	v_mov_b32_e32 v66, v254
	v_mov_b32_e32 v67, v255
	v_lshl_add_u64 v[100:101], s[8:9], 0, v[100:101]
	v_lshl_add_u64 v[100:101], v[180:181], 1, v[100:101]
	v_lshlrev_b32_e32 v106, 16, v102
	v_and_b32_e32 v102, 0xffff0000, v102
	v_add_f32_e32 v61, v61, v102
	v_lshlrev_b32_e32 v102, 16, v103
	v_add_f32_e32 v62, v62, v102
	v_and_b32_e32 v102, 0xffff0000, v103
	v_add_f32_e32 v63, v63, v102
	v_lshlrev_b32_e32 v102, 16, v104
	v_add_f32_e32 v102, v56, v102
	v_and_b32_e32 v56, 0xffff0000, v104
	v_add_f32_e32 v103, v57, v56
	v_lshlrev_b32_e32 v56, 16, v105
	v_add_f32_e32 v104, v58, v56
	v_and_b32_e32 v56, 0xffff0000, v105
	v_add_f32_e32 v60, v60, v106
	v_add_f32_e32 v59, v59, v56
	v_mul_f32_e32 v56, v61, v61
	v_mul_f32_e32 v57, v63, v63
	v_fmac_f32_e32 v56, v60, v60
	v_fmac_f32_e32 v57, v62, v62
	v_add_f32_e32 v56, v56, v57
	v_mul_f32_e32 v57, v103, v103
	v_fmac_f32_e32 v57, v102, v102
	v_add_f32_e32 v56, v57, v56
	v_mul_f32_e32 v57, v59, v59
	v_fmac_f32_e32 v57, v104, v104
	v_add_f32_e32 v105, v57, v56
	v_cvt_pk_bf16_f32 v56, v60, v61
	v_cvt_pk_bf16_f32 v57, v62, v63
	v_cvt_pk_bf16_f32 v58, v102, v103
	v_cvt_pk_bf16_f32 v59, v104, v59
	global_store_dwordx4 v[100:101], v[56:59], off
	s_nop 0
	v_lshlrev_b32_e32 v56, 16, v88
	v_add_f32_e32 v52, v52, v56
	v_and_b32_e32 v56, 0xffff0000, v88
	v_add_f32_e32 v53, v53, v56
	v_lshlrev_b32_e32 v56, 16, v89
	v_add_f32_e32 v54, v54, v56
	v_and_b32_e32 v56, 0xffff0000, v89
	v_add_f32_e32 v55, v55, v56
	v_lshlrev_b32_e32 v56, 16, v90
	v_add_f32_e32 v56, v48, v56
	v_and_b32_e32 v48, 0xffff0000, v90
	v_add_f32_e32 v57, v49, v48
	v_lshlrev_b32_e32 v48, 16, v91
	v_add_f32_e32 v58, v50, v48
	v_and_b32_e32 v48, 0xffff0000, v91
	v_add_f32_e32 v51, v51, v48
	v_mul_f32_e32 v48, v53, v53
	v_mul_f32_e32 v49, v55, v55
	v_fmac_f32_e32 v48, v52, v52
	v_fmac_f32_e32 v49, v54, v54
	v_add_f32_e32 v48, v48, v49
	v_mul_f32_e32 v49, v57, v57
	v_fmac_f32_e32 v49, v56, v56
	v_add_f32_e32 v48, v49, v48
	v_mul_f32_e32 v49, v51, v51
	v_fmac_f32_e32 v49, v58, v58
	v_add_f32_e32 v48, v49, v48
	v_add_f32_e32 v59, v105, v48
	v_cvt_pk_bf16_f32 v48, v52, v53
	v_cvt_pk_bf16_f32 v49, v54, v55
	v_cvt_pk_bf16_f32 v50, v56, v57
	v_cvt_pk_bf16_f32 v51, v58, v51
	global_store_dwordx4 v[100:101], v[48:51], off offset:256
	ds_bpermute_b32 v48, v112, v59
	s_waitcnt lgkmcnt(0)
	v_add_f32_e32 v48, v59, v48
	ds_bpermute_b32 v49, v113, v48
	s_and_saveexec_b64 s[4:5], vcc
	s_cbranch_execz .LBB0_776
	v_lshlrev_b64 v[50:51], 7, v[98:99]
	v_lshl_add_u64 v[50:51], s[10:11], 0, v[50:51]
	v_lshl_add_u64 v[50:51], s[18:19], 2, v[50:51]
	s_lshl_b32 s76, s55, 2
	v_lshl_add_u64 v[50:51], v[50:51], 0, s[76:77]
	s_waitcnt lgkmcnt(0)
	v_add_f32_e32 v48, v48, v49
	global_store_dword v[50:51], v48, off
.LBB0_776:
	s_or_b64 exec, exec, s[4:5]
	v_lshlrev_b32_e32 v50, 16, v84
	v_add_f32_e32 v44, v44, v50
	v_and_b32_e32 v50, 0xffff0000, v84
	v_add_f32_e32 v45, v45, v50
	v_lshlrev_b32_e32 v50, 16, v85
	v_add_f32_e32 v46, v46, v50
	v_and_b32_e32 v50, 0xffff0000, v85
	v_add_f32_e32 v47, v47, v50
	v_lshlrev_b32_e32 v50, 16, v86
	v_add_f32_e32 v50, v40, v50
	v_and_b32_e32 v40, 0xffff0000, v86
	v_add_f32_e32 v51, v41, v40
	v_lshlrev_b32_e32 v40, 16, v87
	v_add_f32_e32 v52, v42, v40
	v_and_b32_e32 v40, 0xffff0000, v87
	v_add_f32_e32 v43, v43, v40
	v_mul_f32_e32 v40, v45, v45
	v_mul_f32_e32 v41, v47, v47
	v_fmac_f32_e32 v40, v44, v44
	v_fmac_f32_e32 v41, v46, v46
	v_add_f32_e32 v40, v40, v41
	v_mul_f32_e32 v41, v51, v51
	v_fmac_f32_e32 v41, v50, v50
	v_add_f32_e32 v40, v41, v40
	v_mul_f32_e32 v41, v43, v43
	v_fmac_f32_e32 v41, v52, v52
	v_add_f32_e32 v42, v41, v40
	v_cvt_pk_bf16_f32 v40, v44, v45
	v_lshlrev_b32_e32 v44, 16, v80
	v_add_f32_e32 v36, v36, v44
	v_and_b32_e32 v44, 0xffff0000, v80
	v_add_f32_e32 v37, v37, v44
	v_lshlrev_b32_e32 v44, 16, v81
	v_add_f32_e32 v38, v38, v44
	v_and_b32_e32 v44, 0xffff0000, v81
	v_add_f32_e32 v39, v39, v44
	v_lshlrev_b32_e32 v44, 16, v82
	v_add_f32_e32 v44, v32, v44
	v_and_b32_e32 v32, 0xffff0000, v82
	v_add_f32_e32 v45, v33, v32
	v_lshlrev_b32_e32 v32, 16, v83
	v_cvt_pk_bf16_f32 v41, v46, v47
	v_add_f32_e32 v46, v34, v32
	v_and_b32_e32 v32, 0xffff0000, v83
	v_add_f32_e32 v47, v35, v32
	v_mul_f32_e32 v32, v37, v37
	v_mul_f32_e32 v33, v39, v39
	v_fmac_f32_e32 v32, v36, v36
	v_fmac_f32_e32 v33, v38, v38
	v_add_f32_e32 v32, v32, v33
	v_mul_f32_e32 v33, v45, v45
	v_fmac_f32_e32 v33, v44, v44
	v_add_f32_e32 v32, v33, v32
	v_mul_f32_e32 v33, v47, v47
	v_fmac_f32_e32 v33, v46, v46
	v_add_f32_e32 v32, v33, v32
	v_add_f32_e32 v32, v42, v32
	ds_bpermute_b32 v33, v112, v32
	s_waitcnt lgkmcnt(1)
	v_lshlrev_b64 v[48:49], 11, v[96:97]
	v_lshl_add_u64 v[48:49], v[48:49], 1, s[8:9]
	v_lshl_add_u64 v[48:49], v[180:181], 1, v[48:49]
	v_cvt_pk_bf16_f32 v42, v50, v51
	s_waitcnt lgkmcnt(0)
	v_add_f32_e32 v32, v32, v33
	ds_bpermute_b32 v33, v113, v32
	v_cvt_pk_bf16_f32 v43, v52, v43
	global_store_dwordx4 v[48:49], v[40:43], off
	v_cvt_pk_bf16_f32 v34, v36, v37
	v_cvt_pk_bf16_f32 v35, v38, v39
	v_cvt_pk_bf16_f32 v36, v44, v45
	v_cvt_pk_bf16_f32 v37, v46, v47
	global_store_dwordx4 v[48:49], v[34:37], off offset:256
	s_and_saveexec_b64 s[4:5], vcc
	s_cbranch_execz .LBB0_778
	v_lshlrev_b64 v[34:35], 7, v[96:97]
	v_lshl_add_u64 v[34:35], s[10:11], 0, v[34:35]
	v_lshl_add_u64 v[34:35], s[18:19], 2, v[34:35]
	s_lshl_b32 s76, s55, 2
	v_lshl_add_u64 v[34:35], v[34:35], 0, s[76:77]
	s_waitcnt lgkmcnt(0)
	v_add_f32_e32 v32, v32, v33
	global_store_dword v[34:35], v32, off
; __device__ __forceinline__ unsigned cvt_pk_bf16(float lo, float hi) { unsigned r; asm volatile("v_cvt_pk_bf16_f32 %0, %1, %2" : "=v"(r) : "v"(lo), "v"(hi)); return r; }
;     __device__ __forceinline__ void operator()(const f32x4 (&acc)[2][2][4][2], const Unit& u, int wr, int wc, int fr, int fq) const {
;     ...
;             for (int m = 0; m < 4; ++m) { const int row = row0 + ai * HALF + m * 16; bf16_t* rowp = X + (size_t)row * ldc + col0;
;                 float part = 0.f;
; #pragma unroll
;                 for (int bj = 0; bj < 2; ++bj) { const u32x4 x4 = xv[m][bj];
;                     const f32x4 a0 = acc[ai][bj][m][0], a1 = acc[ai][bj][m][1];
;                     const float f0 = bflo(x4.x) + a0[0], f1 = bfhi(x4.x) + a0[1], f2 = bflo(x4.y) + a0[2], f3 = bfhi(x4.y) + a0[3];
;                     const float f4 = bflo(x4.z) + a1[0], f5 = bfhi(x4.z) + a1[1], f6 = bflo(x4.w) + a1[2], f7 = bfhi(x4.w) + a1[3];
;                     part += (f0 * f0 + f1 * f1) + (f2 * f2 + f3 * f3) + (f4 * f4 + f5 * f5) + (f6 * f6 + f7 * f7);
;                     u32x4 w; w.x = cvt_pk_bf16(f0, f1); w.y = cvt_pk_bf16(f2, f3); w.z = cvt_pk_bf16(f4, f5); w.w = cvt_pk_bf16(f6, f7);
;                     *(u32x4*)(rowp + bj * HALF) = w; }
;                 part += __shfl_xor(part, 16); part += __shfl_xor(part, 32);
;                 if (fq == 0) SS[(size_t)row * 32 + u.pn * 4 + wc] = part; }
.LBB0_778:
	s_or_b64 exec, exec, s[4:5]
	v_lshlrev_b32_e32 v34, 16, v76
	v_add_f32_e32 v28, v28, v34
	v_and_b32_e32 v34, 0xffff0000, v76
	v_add_f32_e32 v29, v29, v34
	v_lshlrev_b32_e32 v34, 16, v77
	v_add_f32_e32 v30, v30, v34
	v_and_b32_e32 v34, 0xffff0000, v77
	v_add_f32_e32 v31, v31, v34
	v_lshlrev_b32_e32 v34, 16, v78
	v_add_f32_e32 v34, v24, v34
	v_and_b32_e32 v24, 0xffff0000, v78
	v_add_f32_e32 v35, v25, v24
	v_lshlrev_b32_e32 v24, 16, v79
	v_add_f32_e32 v36, v26, v24
	v_and_b32_e32 v24, 0xffff0000, v79
	v_add_f32_e32 v27, v27, v24
	v_mul_f32_e32 v24, v29, v29
	v_mul_f32_e32 v25, v31, v31
	v_fmac_f32_e32 v24, v28, v28
	v_fmac_f32_e32 v25, v30, v30
	v_add_f32_e32 v24, v24, v25
	v_mul_f32_e32 v25, v35, v35
	v_fmac_f32_e32 v25, v34, v34
	v_add_f32_e32 v24, v25, v24
	v_mul_f32_e32 v25, v27, v27
	v_fmac_f32_e32 v25, v36, v36
	v_add_f32_e32 v26, v25, v24
	v_cvt_pk_bf16_f32 v24, v28, v29
	v_lshlrev_b32_e32 v28, 16, v72
	v_add_f32_e32 v20, v20, v28
	v_and_b32_e32 v28, 0xffff0000, v72
	v_add_f32_e32 v21, v21, v28
	v_lshlrev_b32_e32 v28, 16, v73
	v_add_f32_e32 v22, v22, v28
	v_and_b32_e32 v28, 0xffff0000, v73
	v_add_f32_e32 v23, v23, v28
	v_lshlrev_b32_e32 v28, 16, v74
	v_add_f32_e32 v28, v16, v28
	v_and_b32_e32 v16, 0xffff0000, v74
	v_add_f32_e32 v29, v17, v16
	v_lshlrev_b32_e32 v16, 16, v75
	v_cvt_pk_bf16_f32 v25, v30, v31
	v_add_f32_e32 v30, v18, v16
	v_and_b32_e32 v16, 0xffff0000, v75
	v_add_f32_e32 v31, v19, v16
	v_mul_f32_e32 v16, v21, v21
	v_mul_f32_e32 v17, v23, v23
	v_fmac_f32_e32 v16, v20, v20
	v_fmac_f32_e32 v17, v22, v22
	v_add_f32_e32 v16, v16, v17
	v_mul_f32_e32 v17, v29, v29
	v_fmac_f32_e32 v17, v28, v28
	v_add_f32_e32 v16, v17, v16
	v_mul_f32_e32 v17, v31, v31
	v_fmac_f32_e32 v17, v30, v30
	v_add_f32_e32 v16, v17, v16
	v_add_f32_e32 v16, v26, v16
	ds_bpermute_b32 v17, v112, v16
	s_waitcnt lgkmcnt(1)
	v_lshlrev_b64 v[32:33], 11, v[94:95]
	v_lshl_add_u64 v[32:33], v[32:33], 1, s[8:9]
	v_lshl_add_u64 v[32:33], v[180:181], 1, v[32:33]
	v_cvt_pk_bf16_f32 v26, v34, v35
	s_waitcnt lgkmcnt(0)
	v_add_f32_e32 v16, v16, v17
	ds_bpermute_b32 v17, v113, v16
	v_cvt_pk_bf16_f32 v27, v36, v27
	global_store_dwordx4 v[32:33], v[24:27], off
	v_cvt_pk_bf16_f32 v18, v20, v21
	v_cvt_pk_bf16_f32 v19, v22, v23
	v_cvt_pk_bf16_f32 v20, v28, v29
	v_cvt_pk_bf16_f32 v21, v30, v31
	global_store_dwordx4 v[32:33], v[18:21], off offset:256
	s_and_saveexec_b64 s[4:5], vcc
	s_cbranch_execz .LBB0_780
	v_lshlrev_b64 v[18:19], 7, v[94:95]
	v_lshl_add_u64 v[18:19], s[10:11], 0, v[18:19]
	v_lshl_add_u64 v[18:19], s[18:19], 2, v[18:19]
	s_lshl_b32 s76, s55, 2
	v_lshl_add_u64 v[18:19], v[18:19], 0, s[76:77]
	s_waitcnt lgkmcnt(0)
	v_add_f32_e32 v16, v16, v17
	global_store_dword v[18:19], v16, off
.LBB0_780:
	s_or_b64 exec, exec, s[4:5]
	v_lshlrev_b32_e32 v18, 16, v68
	v_add_f32_e32 v12, v12, v18
	v_and_b32_e32 v18, 0xffff0000, v68
	v_add_f32_e32 v13, v13, v18
	v_lshlrev_b32_e32 v18, 16, v69
	v_add_f32_e32 v14, v14, v18
	v_and_b32_e32 v18, 0xffff0000, v69
	v_add_f32_e32 v15, v15, v18
	v_lshlrev_b32_e32 v18, 16, v70
	v_add_f32_e32 v18, v8, v18
	v_and_b32_e32 v8, 0xffff0000, v70
	v_add_f32_e32 v19, v9, v8
	v_lshlrev_b32_e32 v8, 16, v71
	v_add_f32_e32 v20, v10, v8
	v_and_b32_e32 v8, 0xffff0000, v71
	v_add_f32_e32 v11, v11, v8
	v_mul_f32_e32 v8, v13, v13
	v_mul_f32_e32 v9, v15, v15
	v_fmac_f32_e32 v8, v12, v12
	v_fmac_f32_e32 v9, v14, v14
	v_add_f32_e32 v8, v8, v9
	v_mul_f32_e32 v9, v19, v19
	v_fmac_f32_e32 v9, v18, v18
	v_add_f32_e32 v8, v9, v8
	v_mul_f32_e32 v9, v11, v11
	v_fmac_f32_e32 v9, v20, v20
	v_add_f32_e32 v10, v9, v8
	v_cvt_pk_bf16_f32 v8, v12, v13
	v_lshlrev_b32_e32 v12, 16, v64
	v_add_f32_e32 v4, v4, v12
	v_and_b32_e32 v12, 0xffff0000, v64
	v_add_f32_e32 v5, v5, v12
	v_lshlrev_b32_e32 v12, 16, v65
	v_add_f32_e32 v6, v6, v12
	v_and_b32_e32 v12, 0xffff0000, v65
	v_add_f32_e32 v7, v7, v12
	v_lshlrev_b32_e32 v12, 16, v66
	v_add_f32_e32 v12, v0, v12
	v_and_b32_e32 v0, 0xffff0000, v66
	v_add_f32_e32 v13, v1, v0
	v_lshlrev_b32_e32 v0, 16, v67
	v_cvt_pk_bf16_f32 v9, v14, v15
	v_add_f32_e32 v14, v2, v0
	v_and_b32_e32 v0, 0xffff0000, v67
	v_add_f32_e32 v15, v3, v0
	v_mul_f32_e32 v0, v5, v5
	v_mul_f32_e32 v1, v7, v7
	v_fmac_f32_e32 v0, v4, v4
	v_fmac_f32_e32 v1, v6, v6
	v_add_f32_e32 v0, v0, v1
	v_mul_f32_e32 v1, v13, v13
	v_fmac_f32_e32 v1, v12, v12
	v_add_f32_e32 v0, v1, v0
	v_mul_f32_e32 v1, v15, v15
	v_fmac_f32_e32 v1, v14, v14
	v_add_f32_e32 v0, v1, v0
	v_add_f32_e32 v0, v10, v0
	ds_bpermute_b32 v1, v112, v0
	s_waitcnt lgkmcnt(1)
	v_lshlrev_b64 v[16:17], 11, v[92:93]
	v_lshl_add_u64 v[16:17], v[16:17], 1, s[8:9]
	v_lshl_add_u64 v[16:17], v[180:181], 1, v[16:17]
	v_cvt_pk_bf16_f32 v10, v18, v19
	s_waitcnt lgkmcnt(0)
	v_add_f32_e32 v0, v0, v1
	ds_bpermute_b32 v1, v113, v0
	v_cvt_pk_bf16_f32 v11, v20, v11
	global_store_dwordx4 v[16:17], v[8:11], off
	v_cvt_pk_bf16_f32 v2, v4, v5
	v_cvt_pk_bf16_f32 v3, v6, v7
	v_cvt_pk_bf16_f32 v4, v12, v13
	v_cvt_pk_bf16_f32 v5, v14, v15
	global_store_dwordx4 v[16:17], v[2:5], off offset:256
	s_and_saveexec_b64 s[4:5], vcc
	s_cbranch_execz .LBB0_782
	v_lshlrev_b64 v[2:3], 7, v[92:93]
	v_lshl_add_u64 v[2:3], s[10:11], 0, v[2:3]
	v_lshl_add_u64 v[2:3], s[18:19], 2, v[2:3]
	s_lshl_b32 s76, s55, 2
	v_lshl_add_u64 v[2:3], v[2:3], 0, s[76:77]
	s_waitcnt lgkmcnt(0)
	v_add_f32_e32 v0, v0, v1
	global_store_dword v[2:3], v0, off

; __global__ void __launch_bounds__(512, 2) mega(Args a_unused) {
	.amdhsa_kernel _Z4mega4Args
		.amdhsa_group_segment_fixed_size 0
		.amdhsa_private_segment_fixed_size 0
		.amdhsa_kernarg_size 496
		.amdhsa_user_sgpr_count 2
		.amdhsa_user_sgpr_dispatch_ptr 0
		.amdhsa_user_sgpr_queue_ptr 0
		.amdhsa_user_sgpr_kernarg_segment_ptr 1
		.amdhsa_user_sgpr_dispatch_id 0
		.amdhsa_user_sgpr_kernarg_preload_length 0
		.amdhsa_user_sgpr_kernarg_preload_offset 0
		.amdhsa_user_sgpr_private_segment_size 0
		.amdhsa_uses_dynamic_stack 0
		.amdhsa_enable_private_segment 0
		.amdhsa_system_sgpr_workgroup_id_x 1
		.amdhsa_system_sgpr_workgroup_id_y 0
		.amdhsa_system_sgpr_workgroup_id_z 0
		.amdhsa_system_sgpr_workgroup_info 0
		.amdhsa_system_vgpr_workitem_id 2
		.amdhsa_next_free_vgpr 256
		.amdhsa_next_free_sgpr 100
		.amdhsa_accum_offset 256
		.amdhsa_reserve_vcc 1
		.amdhsa_float_round_mode_32 0
		.amdhsa_float_round_mode_16_64 0
		.amdhsa_float_denorm_mode_32 3
		.amdhsa_float_denorm_mode_16_64 3
		.amdhsa_dx10_clamp 1
		.amdhsa_ieee_mode 1
		.amdhsa_fp16_overflow 0
		.amdhsa_tg_split 0
		.amdhsa_exception_fp_ieee_invalid_op 0
		.amdhsa_exception_fp_denorm_src 0
		.amdhsa_exception_fp_ieee_div_zero 0
		.amdhsa_exception_fp_ieee_overflow 0
		.amdhsa_exception_fp_ieee_underflow 0
		.amdhsa_exception_fp_ieee_inexact 0
		.amdhsa_exception_int_div_zero 0
	.end_amdhsa_kernel

; #define a (*get_args())
; __global__ void __launch_bounds__(512, 2) mega(Args a_unused) {
; __global__ void __launch_bounds__(512) k_attn_naive(Args a, int l) { attn_naive((const bf16_t*)(a.ws + WS_Z), a.in[I_SINKS] + l * 16, (bf16_t*)(a.ws + WS_Y)); }
amdhsa.kernels:
  - .agpr_count:     0
    .args:
      - .offset:         0
        .size:           240
        .value_kind:     by_value
      - .offset:         240
        .size:           4
        .value_kind:     hidden_block_count_x
      - .offset:         244
        .size:           4
        .value_kind:     hidden_block_count_y
      - .offset:         248
        .size:           4
        .value_kind:     hidden_block_count_z
      - .offset:         252
        .size:           2
        .value_kind:     hidden_group_size_x
      - .offset:         254
        .size:           2
        .value_kind:     hidden_group_size_y
      - .offset:         256
        .size:           2
        .value_kind:     hidden_group_size_z
      - .offset:         258
        .size:           2
        .value_kind:     hidden_remainder_x
      - .offset:         260
        .size:           2
        .value_kind:     hidden_remainder_y
      - .offset:         262
        .size:           2
        .value_kind:     hidden_remainder_z
      - .offset:         280
        .size:           8
        .value_kind:     hidden_global_offset_x
      - .offset:         288
        .size:           8
        .value_kind:     hidden_global_offset_y
      - .offset:         296
        .size:           8
        .value_kind:     hidden_global_offset_z
      - .offset:         304
        .size:           2
        .value_kind:     hidden_grid_dims
      - .offset:         328
        .size:           8
        .value_kind:     hidden_multigrid_sync_arg
      - .offset:         360
        .size:           4
        .value_kind:     hidden_dynamic_lds_size
    .group_segment_fixed_size: 0
    .kernarg_segment_align: 8
    .kernarg_segment_size: 496
    .language:       OpenCL C
    .language_version:
      - 2
      - 0
    .max_flat_workgroup_size: 512
    .name:           _Z4mega4Args
    .private_segment_fixed_size: 0
    .sgpr_count:     106
    .sgpr_spill_count: 80
    .symbol:         _Z4mega4Args.kd
    .uniform_work_group_size: 1
    .uses_dynamic_stack: false
    .vgpr_count:     256
    .vgpr_spill_count: 0
    .wavefront_size: 64
  - .agpr_count:     0
    .args:
      - .offset:         0
        .size:           240
        .value_kind:     by_value
      - .offset:         240
        .size:           4
        .value_kind:     by_value
      - .offset:         248
        .size:           4
        .value_kind:     hidden_block_count_x
      - .offset:         252
        .size:           4
        .value_kind:     hidden_block_count_y
      - .offset:         256
        .size:           4
        .value_kind:     hidden_block_count_z
      - .offset:         260
        .size:           2
        .value_kind:     hidden_group_size_x
      - .offset:         262
        .size:           2
        .value_kind:     hidden_group_size_y
      - .offset:         264
        .size:           2
        .value_kind:     hidden_group_size_z
      - .offset:         266
        .size:           2
        .value_kind:     hidden_remainder_x
      - .offset:         268
        .size:           2
        .value_kind:     hidden_remainder_y
      - .offset:         270
        .size:           2
        .value_kind:     hidden_remainder_z
      - .offset:         288
        .size:           8
        .value_kind:     hidden_global_offset_x
      - .offset:         296
        .size:           8
        .value_kind:     hidden_global_offset_y
      - .offset:         304
        .size:           8
        .value_kind:     hidden_global_offset_z
      - .offset:         312
        .size:           2
        .value_kind:     hidden_grid_dims
    .group_segment_fixed_size: 0
    .kernarg_segment_align: 8
    .kernarg_segment_size: 504
    .language:       OpenCL C
    .language_version:
      - 2
      - 0
    .max_flat_workgroup_size: 512
    .name:           _Z12k_attn_naive4Argsi
    .private_segment_fixed_size: 0
    .sgpr_count:     28
    .sgpr_spill_count: 0
    .symbol:         _Z12k_attn_naive4Argsi.kd
    .uniform_work_group_size: 1
    .uses_dynamic_stack: false
    .vgpr_count:     166
    .vgpr_spill_count: 0
    .wavefront_size: 64
; #define a (*get_args())
; __global__ void __launch_bounds__(512) k_gmlp_a(Args a, int l) { gmlp_naive_a((const bf16_t*)(a.ws + WS_Z), a.in[I_LN_G] + l * 512, a.in[I_LN_B] + l * 512, (float*)(a.ws + WS_HID), threadIdx.x >> 6, threadIdx.x & 63); }
; __global__ void __launch_bounds__(512) k_gmlp_b(Args a, int l) { gmlp_naive_b((const bf16_t*)(a.ws + WS_Z), (const float*)(a.ws + WS_HID), a.in[I_W_S] + (size_t)l * 4 * 128 * 128, a.in[I_B_S] + l * 512, (bf16_t*)(a.ws + WS_Y)); }
; __global__ void __launch_bounds__(512) k_ssm_naive(Args a, int l) { ssm_naive(a, l, (const bf16_t*)(a.ws + WS_Z), (bf16_t*)(a.ws + WS_YPRE), threadIdx.x >> 6, threadIdx.x & 63); }
  - .agpr_count:     0
    .args:
      - .offset:         0
        .size:           240
        .value_kind:     by_value
      - .offset:         240
        .size:           4
        .value_kind:     by_value
      - .offset:         248
        .size:           4
        .value_kind:     hidden_block_count_x
      - .offset:         252
        .size:           4
        .value_kind:     hidden_block_count_y
      - .offset:         256
        .size:           4
        .value_kind:     hidden_block_count_z
      - .offset:         260
        .size:           2
        .value_kind:     hidden_group_size_x
      - .offset:         262
        .size:           2
        .value_kind:     hidden_group_size_y
      - .offset:         264
        .size:           2
        .value_kind:     hidden_group_size_z
      - .offset:         266
        .size:           2
        .value_kind:     hidden_remainder_x
      - .offset:         268
        .size:           2
        .value_kind:     hidden_remainder_y
      - .offset:         270
        .size:           2
        .value_kind:     hidden_remainder_z
      - .offset:         288
        .size:           8
        .value_kind:     hidden_global_offset_x
      - .offset:         296
        .size:           8
        .value_kind:     hidden_global_offset_y
      - .offset:         304
        .size:           8
        .value_kind:     hidden_global_offset_z
      - .offset:         312
        .size:           2
        .value_kind:     hidden_grid_dims
    .group_segment_fixed_size: 0
    .kernarg_segment_align: 8
    .kernarg_segment_size: 504
    .language:       OpenCL C
    .language_version:
      - 2
      - 0
    .max_flat_workgroup_size: 512
    .name:           _Z8k_gmlp_a4Argsi
    .private_segment_fixed_size: 0
    .sgpr_count:     20
    .sgpr_spill_count: 0
    .symbol:         _Z8k_gmlp_a4Argsi.kd
    .uniform_work_group_size: 1
    .uses_dynamic_stack: false
    .vgpr_count:     45
    .vgpr_spill_count: 0
    .wavefront_size: 64
  - .agpr_count:     0
    .args:
      - .offset:         0
        .size:           240
        .value_kind:     by_value
      - .offset:         240
        .size:           4
        .value_kind:     by_value
      - .offset:         248
        .size:           4
        .value_kind:     hidden_block_count_x
      - .offset:         252
        .size:           4
        .value_kind:     hidden_block_count_y
      - .offset:         256
        .size:           4
        .value_kind:     hidden_block_count_z
      - .offset:         260
        .size:           2
        .value_kind:     hidden_group_size_x
      - .offset:         262
        .size:           2
        .value_kind:     hidden_group_size_y
      - .offset:         264
        .size:           2
        .value_kind:     hidden_group_size_z
      - .offset:         266
        .size:           2
        .value_kind:     hidden_remainder_x
      - .offset:         268
        .size:           2
        .value_kind:     hidden_remainder_y
      - .offset:         270
        .size:           2
        .value_kind:     hidden_remainder_z
      - .offset:         288
        .size:           8
        .value_kind:     hidden_global_offset_x
      - .offset:         296
        .size:           8
        .value_kind:     hidden_global_offset_y
      - .offset:         304
        .size:           8
        .value_kind:     hidden_global_offset_z
      - .offset:         312
        .size:           2
        .value_kind:     hidden_grid_dims
    .group_segment_fixed_size: 0
    .kernarg_segment_align: 8
    .kernarg_segment_size: 504
    .language:       OpenCL C
    .language_version:
      - 2
      - 0
    .max_flat_workgroup_size: 512
    .name:           _Z8k_gmlp_b4Argsi
    .private_segment_fixed_size: 0
    .sgpr_count:     24
    .sgpr_spill_count: 0
    .symbol:         _Z8k_gmlp_b4Argsi.kd
    .uniform_work_group_size: 1
    .uses_dynamic_stack: false
    .vgpr_count:     22
    .vgpr_spill_count: 0
    .wavefront_size: 64
  - .agpr_count:     0
    .args:
      - .offset:         0
        .size:           240
        .value_kind:     by_value
      - .offset:         240
        .size:           4
        .value_kind:     by_value
      - .offset:         248
        .size:           4
        .value_kind:     hidden_block_count_x
      - .offset:         252
        .size:           4
        .value_kind:     hidden_block_count_y
      - .offset:         256
        .size:           4
        .value_kind:     hidden_block_count_z
      - .offset:         260
        .size:           2
        .value_kind:     hidden_group_size_x
      - .offset:         262
        .size:           2
        .value_kind:     hidden_group_size_y
      - .offset:         264
        .size:           2
        .value_kind:     hidden_group_size_z
      - .offset:         266
        .size:           2
        .value_kind:     hidden_remainder_x
      - .offset:         268
        .size:           2
        .value_kind:     hidden_remainder_y
      - .offset:         270
        .size:           2
        .value_kind:     hidden_remainder_z
      - .offset:         288
        .size:           8
        .value_kind:     hidden_global_offset_x
      - .offset:         296
        .size:           8
        .value_kind:     hidden_global_offset_y
      - .offset:         304
        .size:           8
        .value_kind:     hidden_global_offset_z
      - .offset:         312
        .size:           2
        .value_kind:     hidden_grid_dims
    .group_segment_fixed_size: 0
    .kernarg_segment_align: 8
    .kernarg_segment_size: 504
    .language:       OpenCL C
    .language_version:
      - 2
      - 0
    .max_flat_workgroup_size: 512
    .name:           _Z11k_ssm_naive4Argsi
    .private_segment_fixed_size: 0
    .sgpr_count:     42
    .sgpr_spill_count: 0
    .symbol:         _Z11k_ssm_naive4Argsi.kd
    .uniform_work_group_size: 1
    .uses_dynamic_stack: false
    .vgpr_count:     128
    .vgpr_spill_count: 0
    .wavefront_size: 64
